# K-loops: loop-back pointer/counter SALU rotated in front of the loop-back barrier; B fragment reads through one base VGPR + immediate offsets (4 VALU address adds per iteration removed)
# speedup vs baseline: 1.0002x; 1.0002x over previous
.LBB0_316:
	s_cmp_eq_u32 s8, 0
	s_cselect_b64 s[68:69], -1, 0
	s_add_u32 s8, s42, 0x100
	s_addc_u32 s92, s43, 0
	v_mov_b32_e32 v128, v129
	s_add_u32 s93, s72, 0x100
	v_mov_b32_e32 v130, v129
	v_mov_b32_e32 v131, v129
	v_mov_b32_e32 v64, 0
	s_waitcnt lgkmcnt(0)
	v_mov_b64_e32 v[0:1], v[128:129]
	v_mov_b64_e32 v[4:5], v[128:129]
	v_mov_b64_e32 v[16:17], v[128:129]
	v_mov_b64_e32 v[20:21], v[128:129]
	v_mov_b64_e32 v[32:33], v[128:129]
	v_mov_b64_e32 v[36:37], v[128:129]
	v_mov_b64_e32 v[48:49], v[128:129]
	v_mov_b64_e32 v[52:53], v[128:129]
	v_mov_b64_e32 v[8:9], v[128:129]
	v_mov_b64_e32 v[12:13], v[128:129]
	v_mov_b64_e32 v[24:25], v[128:129]
	v_mov_b64_e32 v[28:29], v[128:129]
	v_mov_b64_e32 v[40:41], v[128:129]
	v_mov_b64_e32 v[44:45], v[128:129]
	v_mov_b64_e32 v[56:57], v[128:129]
	v_mov_b64_e32 v[60:61], v[128:129]
	s_mov_b32 s3, 0
	s_addc_u32 s94, s73, 0
	v_mov_b64_e32 v[2:3], v[130:131]
	v_mov_b64_e32 v[6:7], v[130:131]
	v_mov_b64_e32 v[18:19], v[130:131]
	v_mov_b64_e32 v[22:23], v[130:131]
	v_mov_b64_e32 v[34:35], v[130:131]
	v_mov_b64_e32 v[38:39], v[130:131]
	v_mov_b64_e32 v[50:51], v[130:131]
	v_mov_b64_e32 v[54:55], v[130:131]
	v_mov_b64_e32 v[10:11], v[130:131]
	v_mov_b64_e32 v[14:15], v[130:131]
	v_mov_b64_e32 v[26:27], v[130:131]
	v_mov_b64_e32 v[30:31], v[130:131]
	v_mov_b64_e32 v[42:43], v[130:131]
	v_mov_b64_e32 v[46:47], v[130:131]
	v_mov_b64_e32 v[58:59], v[130:131]
	v_mov_b64_e32 v[62:63], v[130:131]
	v_mov_b32_e32 v65, v64
	v_mov_b32_e32 v66, v64
	v_mov_b32_e32 v67, v64
	v_mov_b32_e32 v68, v64
	v_mov_b32_e32 v69, v64
	v_mov_b32_e32 v70, v64
	v_mov_b32_e32 v71, v64
	v_mov_b32_e32 v80, v64
	v_mov_b32_e32 v81, v64
	v_mov_b32_e32 v82, v64
	v_mov_b32_e32 v83, v64
	v_mov_b32_e32 v84, v64
	v_mov_b32_e32 v85, v64
	v_mov_b32_e32 v86, v64
	v_mov_b32_e32 v87, v64
	v_mov_b32_e32 v96, v64
	v_mov_b32_e32 v97, v64
	v_mov_b32_e32 v98, v64
	v_mov_b32_e32 v99, v64
	v_mov_b32_e32 v100, v64
	v_mov_b32_e32 v101, v64
	v_mov_b32_e32 v102, v64
	v_mov_b32_e32 v103, v64
	v_mov_b32_e32 v112, v64
	v_mov_b32_e32 v113, v64
	v_mov_b32_e32 v114, v64
	v_mov_b32_e32 v115, v64
	v_mov_b32_e32 v116, v64
	v_mov_b32_e32 v117, v64
	v_mov_b32_e32 v118, v64
	v_mov_b32_e32 v119, v64
	v_mov_b32_e32 v72, v64
	v_mov_b32_e32 v73, v64
	v_mov_b32_e32 v74, v64
	v_mov_b32_e32 v75, v64
	v_mov_b32_e32 v76, v64
	v_mov_b32_e32 v77, v64
	v_mov_b32_e32 v78, v64
	v_mov_b32_e32 v79, v64
	v_mov_b32_e32 v88, v64
	v_mov_b32_e32 v89, v64
	v_mov_b32_e32 v90, v64
	v_mov_b32_e32 v91, v64
	v_mov_b32_e32 v92, v64
	v_mov_b32_e32 v93, v64
	v_mov_b32_e32 v94, v64
	v_mov_b32_e32 v95, v64
	v_mov_b32_e32 v104, v64
	v_mov_b32_e32 v105, v64
	v_mov_b32_e32 v106, v64
	v_mov_b32_e32 v107, v64
	v_mov_b32_e32 v108, v64
	v_mov_b32_e32 v109, v64
	v_mov_b32_e32 v110, v64
	v_mov_b32_e32 v111, v64
	v_mov_b32_e32 v120, v64
	v_mov_b32_e32 v121, v64
	v_mov_b32_e32 v122, v64
	v_mov_b32_e32 v123, v64
	v_mov_b32_e32 v124, v64
	v_mov_b32_e32 v125, v64
	v_mov_b32_e32 v126, v64
	v_mov_b32_e32 v127, v64
	v_add_u32_e32 v194, 0x10000, v251
	s_branch .LBB0_318
.LBB0_317:
	s_add_i32 s3, s3, 2
	s_add_u32 s8, s8, 0x100
	s_addc_u32 s92, s92, 0
	s_add_u32 s93, s93, 0x100
	s_addc_u32 s94, s94, 0
	s_cmp_ge_u32 s3, s22
	s_barrier
	s_cbranch_scc1 .LBB0_322
.LBB0_318:
	ds_read_b128 v[146:149], v194
	ds_read_b128 v[150:153], v194 offset:1024
	ds_read_b128 v[154:157], v194 offset:2048
	ds_read_b128 v[158:161], v194 offset:3072
	ds_read_b128 v[130:133], v194 offset:16384
	ds_read_b128 v[134:137], v194 offset:17408
	ds_read_b128 v[138:141], v194 offset:18432
	ds_read_b128 v[142:145], v194 offset:19456
	s_add_u32 s42, s93, s9
	s_addc_u32 s43, s94, 0
	s_add_u32 s42, s42, 0xffffff80
	s_addc_u32 s43, s43, -1
	s_mov_b32 s74, m0
	s_mov_b32 m0, s65
	s_nop 0
	global_load_lds_dwordx4 v245, s[42:43]
	s_mov_b32 m0, s74
	s_nop 0
	s_mov_b32 s74, m0
	s_mov_b32 m0, s66
	s_nop 0
	global_load_lds_dwordx4 v247, s[42:43]
	s_mov_b32 m0, s74
	s_cmp_eq_u32 s57, s3
	s_cselect_b32 s73, s55, s94
	s_cselect_b32 s72, s54, s93
	s_cselect_b32 s77, s63, s92
	s_cselect_b32 s76, s62, s8
	s_waitcnt lgkmcnt(0)
	ds_read_b128 v[162:165], v252
	ds_read_b128 v[166:169], v252 offset:1024
	ds_read_b128 v[170:173], v252 offset:2048
	ds_read_b128 v[174:177], v252 offset:3072
	ds_read_b128 v[178:181], v252 offset:4096
	ds_read_b128 v[182:185], v252 offset:5120
	ds_read_b128 v[186:189], v252 offset:6144
	ds_read_b128 v[190:193], v252 offset:7168
	s_waitcnt vmcnt(8)
	s_waitcnt lgkmcnt(0)
	s_barrier
	s_setprio 1
	s_waitcnt lgkmcnt(0)
	v_mfma_f32_16x16x32_bf16 v[124:127], v[146:149], v[162:165], v[124:127]
	v_mfma_f32_16x16x32_bf16 v[120:123], v[154:157], v[162:165], v[120:123]
	v_mfma_f32_16x16x32_bf16 v[108:111], v[146:149], v[170:173], v[108:111]
	v_mfma_f32_16x16x32_bf16 v[104:107], v[154:157], v[170:173], v[104:107]
	v_mfma_f32_16x16x32_bf16 v[92:95], v[146:149], v[178:181], v[92:95]
	v_mfma_f32_16x16x32_bf16 v[88:91], v[154:157], v[178:181], v[88:91]
	v_mfma_f32_16x16x32_bf16 v[76:79], v[146:149], v[186:189], v[76:79]
	v_mfma_f32_16x16x32_bf16 v[72:75], v[154:157], v[186:189], v[72:75]
	v_mfma_f32_16x16x32_bf16 v[124:127], v[150:153], v[166:169], v[124:127]
	v_mfma_f32_16x16x32_bf16 v[120:123], v[158:161], v[166:169], v[120:123]
	v_mfma_f32_16x16x32_bf16 v[108:111], v[150:153], v[174:177], v[108:111]
	v_mfma_f32_16x16x32_bf16 v[104:107], v[158:161], v[174:177], v[104:107]
	v_mfma_f32_16x16x32_bf16 v[92:95], v[150:153], v[182:185], v[92:95]
	v_mfma_f32_16x16x32_bf16 v[88:91], v[158:161], v[182:185], v[88:91]
	v_mfma_f32_16x16x32_bf16 v[76:79], v[150:153], v[190:193], v[76:79]
	v_mfma_f32_16x16x32_bf16 v[72:75], v[158:161], v[190:193], v[72:75]
	s_setprio 0
	s_setprio 1
	v_mfma_f32_16x16x32_bf16 v[116:119], v[130:133], v[162:165], v[116:119]
	v_mfma_f32_16x16x32_bf16 v[112:115], v[138:141], v[162:165], v[112:115]
	v_mfma_f32_16x16x32_bf16 v[100:103], v[130:133], v[170:173], v[100:103]
	v_mfma_f32_16x16x32_bf16 v[96:99], v[138:141], v[170:173], v[96:99]
	v_mfma_f32_16x16x32_bf16 v[84:87], v[130:133], v[178:181], v[84:87]
	v_mfma_f32_16x16x32_bf16 v[80:83], v[138:141], v[178:181], v[80:83]
	v_mfma_f32_16x16x32_bf16 v[68:71], v[130:133], v[186:189], v[68:71]
	v_mfma_f32_16x16x32_bf16 v[64:67], v[138:141], v[186:189], v[64:67]
	v_mfma_f32_16x16x32_bf16 v[116:119], v[134:137], v[166:169], v[116:119]
	v_mfma_f32_16x16x32_bf16 v[112:115], v[142:145], v[166:169], v[112:115]
	v_mfma_f32_16x16x32_bf16 v[100:103], v[134:137], v[174:177], v[100:103]
	v_mfma_f32_16x16x32_bf16 v[96:99], v[142:145], v[174:177], v[96:99]
	v_mfma_f32_16x16x32_bf16 v[84:87], v[134:137], v[182:185], v[84:87]
	v_mfma_f32_16x16x32_bf16 v[80:83], v[142:145], v[182:185], v[80:83]
	v_mfma_f32_16x16x32_bf16 v[68:71], v[134:137], v[190:193], v[68:71]
	v_mfma_f32_16x16x32_bf16 v[64:67], v[142:145], v[190:193], v[64:67]
	s_setprio 0
	s_barrier
	s_mov_b32 s42, m0
	s_mov_b32 m0, s14
	s_nop 0
	global_load_lds_dwordx4 v246, s[76:77]
	s_mov_b32 m0, s42
	s_add_u32 s74, s76, s9
	s_mov_b32 s42, m0
	s_mov_b32 m0, s15
	s_nop 0
	global_load_lds_dwordx4 v248, s[76:77]
	s_mov_b32 m0, s42
	s_addc_u32 s75, s77, 0
	s_mov_b32 s42, m0
	s_mov_b32 m0, s16
	s_nop 0
	global_load_lds_dwordx4 v246, s[74:75]
	s_mov_b32 m0, s42
	v_cndmask_b32_e64 v128, 0, 1, s[68:69]
	s_mov_b32 s42, m0
	s_mov_b32 m0, s17
	s_nop 0
	global_load_lds_dwordx4 v248, s[74:75]
	s_mov_b32 m0, s42
	s_andn2_b64 vcc, exec, s[68:69]
	s_mov_b32 s42, m0
	s_mov_b32 m0, s11
	s_nop 0
	global_load_lds_dwordx4 v245, s[72:73]
	s_mov_b32 m0, s42
	s_nop 0
	s_mov_b32 s42, m0
	s_mov_b32 m0, s19
	s_nop 0
	global_load_lds_dwordx4 v247, s[72:73]
	s_mov_b32 m0, s42
	ds_read_b128 v[186:189], v252 offset:16384
	ds_read_b128 v[190:193], v252 offset:17408
	ds_read_b128 v[178:181], v252 offset:18432
	ds_read_b128 v[182:185], v252 offset:19456
	ds_read_b128 v[170:173], v252 offset:20480
	ds_read_b128 v[174:177], v252 offset:21504
	ds_read_b128 v[162:165], v252 offset:22528
	ds_read_b128 v[166:169], v252 offset:23552
	s_waitcnt vmcnt(8)
	s_waitcnt lgkmcnt(0)
	s_barrier
	v_cmp_ne_u32_e64 s[42:43], 1, v128
	s_cbranch_vccnz .LBB0_320
	s_setprio 1
	s_waitcnt lgkmcnt(0)
	v_mfma_f32_16x16x32_bf16 v[60:63], v[146:149], v[186:189], v[60:63]
	v_mfma_f32_16x16x32_bf16 v[56:59], v[154:157], v[186:189], v[56:59]
	v_mfma_f32_16x16x32_bf16 v[44:47], v[146:149], v[178:181], v[44:47]
	v_mfma_f32_16x16x32_bf16 v[40:43], v[154:157], v[178:181], v[40:43]
	v_mfma_f32_16x16x32_bf16 v[28:31], v[146:149], v[170:173], v[28:31]
	v_mfma_f32_16x16x32_bf16 v[24:27], v[154:157], v[170:173], v[24:27]
	v_mfma_f32_16x16x32_bf16 v[12:15], v[146:149], v[162:165], v[12:15]
	v_mfma_f32_16x16x32_bf16 v[8:11], v[154:157], v[162:165], v[8:11]
	v_mfma_f32_16x16x32_bf16 v[60:63], v[150:153], v[190:193], v[60:63]
	v_mfma_f32_16x16x32_bf16 v[56:59], v[158:161], v[190:193], v[56:59]
	v_mfma_f32_16x16x32_bf16 v[44:47], v[150:153], v[182:185], v[44:47]
	v_mfma_f32_16x16x32_bf16 v[40:43], v[158:161], v[182:185], v[40:43]
	v_mfma_f32_16x16x32_bf16 v[28:31], v[150:153], v[174:177], v[28:31]
	v_mfma_f32_16x16x32_bf16 v[24:27], v[158:161], v[174:177], v[24:27]
	v_mfma_f32_16x16x32_bf16 v[12:15], v[150:153], v[166:169], v[12:15]
	v_mfma_f32_16x16x32_bf16 v[8:11], v[158:161], v[166:169], v[8:11]
	s_setprio 0
	s_setprio 1
	v_mfma_f32_16x16x32_bf16 v[52:55], v[130:133], v[186:189], v[52:55]
	v_mfma_f32_16x16x32_bf16 v[48:51], v[138:141], v[186:189], v[48:51]
	v_mfma_f32_16x16x32_bf16 v[36:39], v[130:133], v[178:181], v[36:39]
	v_mfma_f32_16x16x32_bf16 v[32:35], v[138:141], v[178:181], v[32:35]
	v_mfma_f32_16x16x32_bf16 v[20:23], v[130:133], v[170:173], v[20:23]
	v_mfma_f32_16x16x32_bf16 v[16:19], v[138:141], v[170:173], v[16:19]
	v_mfma_f32_16x16x32_bf16 v[4:7], v[130:133], v[162:165], v[4:7]
	v_mfma_f32_16x16x32_bf16 v[0:3], v[138:141], v[162:165], v[0:3]
	v_mfma_f32_16x16x32_bf16 v[52:55], v[134:137], v[190:193], v[52:55]
	v_mfma_f32_16x16x32_bf16 v[48:51], v[142:145], v[190:193], v[48:51]
	v_mfma_f32_16x16x32_bf16 v[36:39], v[134:137], v[182:185], v[36:39]
	v_mfma_f32_16x16x32_bf16 v[32:35], v[142:145], v[182:185], v[32:35]
	v_mfma_f32_16x16x32_bf16 v[20:23], v[134:137], v[174:177], v[20:23]
	v_mfma_f32_16x16x32_bf16 v[16:19], v[142:145], v[174:177], v[16:19]
	v_mfma_f32_16x16x32_bf16 v[4:7], v[134:137], v[166:169], v[4:7]
	v_mfma_f32_16x16x32_bf16 v[0:3], v[142:145], v[166:169], v[0:3]
	s_setprio 0
.LBB0_320:
	s_add_u32 s80, s72, 0x80
	s_addc_u32 s81, s73, 0
	s_add_u32 s76, s76, 0x80
	s_addc_u32 s77, s77, 0
	s_barrier
	ds_read_b128 v[146:149], v194 offset:32768
	ds_read_b128 v[150:153], v194 offset:33792
	ds_read_b128 v[154:157], v194 offset:34816
	ds_read_b128 v[158:161], v194 offset:35840
	ds_read_b128 v[130:133], v194 offset:49152
	ds_read_b128 v[134:137], v194 offset:50176
	ds_read_b128 v[138:141], v194 offset:51200
	ds_read_b128 v[142:145], v194 offset:52224
	s_add_u32 s72, s72, s9
	s_addc_u32 s73, s73, 0
	s_mov_b32 s95, m0
	s_mov_b32 m0, s20
	s_nop 0
	global_load_lds_dwordx4 v245, s[72:73]
	s_mov_b32 m0, s95
	s_nop 0
	s_mov_b32 s95, m0
	s_mov_b32 m0, s21
	s_nop 0
	global_load_lds_dwordx4 v247, s[72:73]
	s_mov_b32 m0, s95
	s_waitcnt lgkmcnt(0)
	ds_read_b128 v[162:165], v252 offset:32768
	ds_read_b128 v[166:169], v252 offset:33792
	ds_read_b128 v[170:173], v252 offset:34816
	ds_read_b128 v[174:177], v252 offset:35840
	ds_read_b128 v[178:181], v252 offset:36864
	ds_read_b128 v[182:185], v252 offset:37888
	ds_read_b128 v[186:189], v252 offset:38912
	ds_read_b128 v[190:193], v252 offset:39936
	s_waitcnt vmcnt(8)
	s_waitcnt lgkmcnt(0)
	s_barrier
	s_setprio 1
	s_waitcnt lgkmcnt(0)
	v_mfma_f32_16x16x32_bf16 v[124:127], v[146:149], v[162:165], v[124:127]
	v_mfma_f32_16x16x32_bf16 v[120:123], v[154:157], v[162:165], v[120:123]
	v_mfma_f32_16x16x32_bf16 v[108:111], v[146:149], v[170:173], v[108:111]
	v_mfma_f32_16x16x32_bf16 v[104:107], v[154:157], v[170:173], v[104:107]
	v_mfma_f32_16x16x32_bf16 v[92:95], v[146:149], v[178:181], v[92:95]
	v_mfma_f32_16x16x32_bf16 v[88:91], v[154:157], v[178:181], v[88:91]
	v_mfma_f32_16x16x32_bf16 v[76:79], v[146:149], v[186:189], v[76:79]
	v_mfma_f32_16x16x32_bf16 v[72:75], v[154:157], v[186:189], v[72:75]
	v_mfma_f32_16x16x32_bf16 v[124:127], v[150:153], v[166:169], v[124:127]
	v_mfma_f32_16x16x32_bf16 v[120:123], v[158:161], v[166:169], v[120:123]
	v_mfma_f32_16x16x32_bf16 v[108:111], v[150:153], v[174:177], v[108:111]
	v_mfma_f32_16x16x32_bf16 v[104:107], v[158:161], v[174:177], v[104:107]
	v_mfma_f32_16x16x32_bf16 v[92:95], v[150:153], v[182:185], v[92:95]
	v_mfma_f32_16x16x32_bf16 v[88:91], v[158:161], v[182:185], v[88:91]
	v_mfma_f32_16x16x32_bf16 v[76:79], v[150:153], v[190:193], v[76:79]
	v_mfma_f32_16x16x32_bf16 v[72:75], v[158:161], v[190:193], v[72:75]
	s_setprio 0
	s_setprio 1
	v_mfma_f32_16x16x32_bf16 v[116:119], v[130:133], v[162:165], v[116:119]
	v_mfma_f32_16x16x32_bf16 v[112:115], v[138:141], v[162:165], v[112:115]
	v_mfma_f32_16x16x32_bf16 v[100:103], v[130:133], v[170:173], v[100:103]
	v_mfma_f32_16x16x32_bf16 v[96:99], v[138:141], v[170:173], v[96:99]
	v_mfma_f32_16x16x32_bf16 v[84:87], v[130:133], v[178:181], v[84:87]
	v_mfma_f32_16x16x32_bf16 v[80:83], v[138:141], v[178:181], v[80:83]
	v_mfma_f32_16x16x32_bf16 v[68:71], v[130:133], v[186:189], v[68:71]
	v_mfma_f32_16x16x32_bf16 v[64:67], v[138:141], v[186:189], v[64:67]
	v_mfma_f32_16x16x32_bf16 v[116:119], v[134:137], v[166:169], v[116:119]
	v_mfma_f32_16x16x32_bf16 v[112:115], v[142:145], v[166:169], v[112:115]
	v_mfma_f32_16x16x32_bf16 v[100:103], v[134:137], v[174:177], v[100:103]
	v_mfma_f32_16x16x32_bf16 v[96:99], v[142:145], v[174:177], v[96:99]
	v_mfma_f32_16x16x32_bf16 v[84:87], v[134:137], v[182:185], v[84:87]
	v_mfma_f32_16x16x32_bf16 v[80:83], v[142:145], v[182:185], v[80:83]
	v_mfma_f32_16x16x32_bf16 v[68:71], v[134:137], v[190:193], v[68:71]
	v_mfma_f32_16x16x32_bf16 v[64:67], v[142:145], v[190:193], v[64:67]
	s_setprio 0
	s_barrier
	s_mov_b32 s72, m0
	s_mov_b32 m0, s23
	s_nop 0
	global_load_lds_dwordx4 v246, s[76:77]
	s_mov_b32 m0, s72
	s_nop 0
	s_mov_b32 s72, m0
	s_mov_b32 m0, s30
	s_nop 0
	global_load_lds_dwordx4 v248, s[76:77]
	s_mov_b32 m0, s72
	s_add_u32 s72, s74, 0x80
	s_addc_u32 s73, s75, 0
	s_mov_b32 s74, m0
	s_mov_b32 m0, s52
	s_nop 0
	global_load_lds_dwordx4 v246, s[72:73]
	s_mov_b32 m0, s74
	s_and_b64 vcc, exec, s[42:43]
	s_mov_b32 s74, m0
	s_mov_b32 m0, s53
	s_nop 0
	global_load_lds_dwordx4 v248, s[72:73]
	s_mov_b32 m0, s74
	s_mov_b32 s72, m0
	s_mov_b32 m0, s47
	s_nop 0
	global_load_lds_dwordx4 v245, s[80:81]
	s_mov_b32 m0, s72
	s_nop 0
	s_mov_b32 s72, m0
	s_mov_b32 m0, s50
	s_nop 0
	global_load_lds_dwordx4 v247, s[80:81]
	s_mov_b32 m0, s72
	ds_read_b128 v[186:189], v252 offset:49152
	ds_read_b128 v[190:193], v252 offset:50176
	ds_read_b128 v[178:181], v252 offset:51200
	ds_read_b128 v[182:185], v252 offset:52224
	ds_read_b128 v[170:173], v252 offset:53248
	ds_read_b128 v[174:177], v252 offset:54272
	ds_read_b128 v[162:165], v252 offset:55296
	ds_read_b128 v[166:169], v252 offset:56320
	s_waitcnt vmcnt(8)
	s_waitcnt lgkmcnt(0)
	s_barrier
	s_cbranch_vccnz .LBB0_317
	s_setprio 1
	s_waitcnt lgkmcnt(0)
	v_mfma_f32_16x16x32_bf16 v[60:63], v[146:149], v[186:189], v[60:63]
	v_mfma_f32_16x16x32_bf16 v[56:59], v[154:157], v[186:189], v[56:59]
	v_mfma_f32_16x16x32_bf16 v[44:47], v[146:149], v[178:181], v[44:47]
	v_mfma_f32_16x16x32_bf16 v[40:43], v[154:157], v[178:181], v[40:43]
	v_mfma_f32_16x16x32_bf16 v[28:31], v[146:149], v[170:173], v[28:31]
	v_mfma_f32_16x16x32_bf16 v[24:27], v[154:157], v[170:173], v[24:27]
	v_mfma_f32_16x16x32_bf16 v[12:15], v[146:149], v[162:165], v[12:15]
	v_mfma_f32_16x16x32_bf16 v[8:11], v[154:157], v[162:165], v[8:11]
	v_mfma_f32_16x16x32_bf16 v[60:63], v[150:153], v[190:193], v[60:63]
	v_mfma_f32_16x16x32_bf16 v[56:59], v[158:161], v[190:193], v[56:59]
	v_mfma_f32_16x16x32_bf16 v[44:47], v[150:153], v[182:185], v[44:47]
	v_mfma_f32_16x16x32_bf16 v[40:43], v[158:161], v[182:185], v[40:43]
	v_mfma_f32_16x16x32_bf16 v[28:31], v[150:153], v[174:177], v[28:31]
	v_mfma_f32_16x16x32_bf16 v[24:27], v[158:161], v[174:177], v[24:27]
	v_mfma_f32_16x16x32_bf16 v[12:15], v[150:153], v[166:169], v[12:15]
	v_mfma_f32_16x16x32_bf16 v[8:11], v[158:161], v[166:169], v[8:11]
	s_setprio 0
	s_setprio 1
	v_mfma_f32_16x16x32_bf16 v[52:55], v[130:133], v[186:189], v[52:55]
	v_mfma_f32_16x16x32_bf16 v[48:51], v[138:141], v[186:189], v[48:51]
	v_mfma_f32_16x16x32_bf16 v[36:39], v[130:133], v[178:181], v[36:39]
	v_mfma_f32_16x16x32_bf16 v[32:35], v[138:141], v[178:181], v[32:35]
	v_mfma_f32_16x16x32_bf16 v[20:23], v[130:133], v[170:173], v[20:23]
	v_mfma_f32_16x16x32_bf16 v[16:19], v[138:141], v[170:173], v[16:19]
	v_mfma_f32_16x16x32_bf16 v[4:7], v[130:133], v[162:165], v[4:7]
	v_mfma_f32_16x16x32_bf16 v[0:3], v[138:141], v[162:165], v[0:3]
	v_mfma_f32_16x16x32_bf16 v[52:55], v[134:137], v[190:193], v[52:55]
	v_mfma_f32_16x16x32_bf16 v[48:51], v[142:145], v[190:193], v[48:51]
	v_mfma_f32_16x16x32_bf16 v[36:39], v[134:137], v[182:185], v[36:39]
	v_mfma_f32_16x16x32_bf16 v[32:35], v[142:145], v[182:185], v[32:35]
	v_mfma_f32_16x16x32_bf16 v[20:23], v[134:137], v[174:177], v[20:23]
	v_mfma_f32_16x16x32_bf16 v[16:19], v[142:145], v[174:177], v[16:19]
	v_mfma_f32_16x16x32_bf16 v[4:7], v[134:137], v[166:169], v[4:7]
	v_mfma_f32_16x16x32_bf16 v[0:3], v[142:145], v[166:169], v[0:3]
	s_setprio 0
	s_branch .LBB0_317

.LBB0_411:
	s_ashr_i32 s27, s26, 31
	s_lshl_b64 s[18:19], s[26:27], 19
	v_readlane_b32 s3, v255, 25
	s_add_u32 s3, s3, s18
	v_readlane_b32 s18, v255, 26
	s_addc_u32 s18, s18, s19
	s_lshl_b32 s19, s57, 18
	s_add_u32 s48, s3, s19
	s_addc_u32 s49, s18, 0
	s_and_b64 s[18:19], s[36:37], exec
	s_cselect_b32 s27, s49, s47
	s_cselect_b32 s99, s48, s46
	s_ashr_i32 s23, s22, 31
	s_lshl_b64 s[18:19], s[22:23], 19
	s_add_u32 s54, s6, s18
	s_addc_u32 s55, s7, s19
	s_and_b64 s[18:19], s[36:37], exec
	s_cselect_b32 s23, s55, s45
	s_cselect_b32 s3, s54, s44
	s_cmp_eq_u32 s8, 0
	s_cselect_b64 s[72:73], -1, 0
	s_add_u32 s8, s44, 0x100
	s_addc_u32 s18, s45, 0
	v_mov_b32_e32 v128, v129
	s_add_u32 s46, s46, 0x40080
	s_waitcnt lgkmcnt(0)
	v_mov_b32_e32 v130, v129
	v_mov_b32_e32 v131, v129
	v_mov_b32_e32 v64, 0
	v_mov_b64_e32 v[0:1], v[128:129]
	v_mov_b64_e32 v[4:5], v[128:129]
	v_mov_b64_e32 v[16:17], v[128:129]
	v_mov_b64_e32 v[20:21], v[128:129]
	v_mov_b64_e32 v[32:33], v[128:129]
	v_mov_b64_e32 v[36:37], v[128:129]
	v_mov_b64_e32 v[48:49], v[128:129]
	v_mov_b64_e32 v[52:53], v[128:129]
	v_mov_b64_e32 v[8:9], v[128:129]
	v_mov_b64_e32 v[12:13], v[128:129]
	v_mov_b64_e32 v[24:25], v[128:129]
	v_mov_b64_e32 v[28:29], v[128:129]
	v_mov_b64_e32 v[40:41], v[128:129]
	v_mov_b64_e32 v[44:45], v[128:129]
	v_mov_b64_e32 v[56:57], v[128:129]
	v_mov_b64_e32 v[60:61], v[128:129]
	s_addc_u32 s47, s47, 0
	s_mov_b32 s19, -2
	v_mov_b64_e32 v[2:3], v[130:131]
	v_mov_b64_e32 v[6:7], v[130:131]
	v_mov_b64_e32 v[18:19], v[130:131]
	v_mov_b64_e32 v[22:23], v[130:131]
	v_mov_b64_e32 v[34:35], v[130:131]
	v_mov_b64_e32 v[38:39], v[130:131]
	v_mov_b64_e32 v[50:51], v[130:131]
	v_mov_b64_e32 v[54:55], v[130:131]
	v_mov_b64_e32 v[10:11], v[130:131]
	v_mov_b64_e32 v[14:15], v[130:131]
	v_mov_b64_e32 v[26:27], v[130:131]
	v_mov_b64_e32 v[30:31], v[130:131]
	v_mov_b64_e32 v[42:43], v[130:131]
	v_mov_b64_e32 v[46:47], v[130:131]
	v_mov_b64_e32 v[58:59], v[130:131]
	v_mov_b64_e32 v[62:63], v[130:131]
	v_mov_b32_e32 v65, v64
	v_mov_b32_e32 v66, v64
	v_mov_b32_e32 v67, v64
	v_mov_b32_e32 v68, v64
	v_mov_b32_e32 v69, v64
	v_mov_b32_e32 v70, v64
	v_mov_b32_e32 v71, v64
	v_mov_b32_e32 v80, v64
	v_mov_b32_e32 v81, v64
	v_mov_b32_e32 v82, v64
	v_mov_b32_e32 v83, v64
	v_mov_b32_e32 v84, v64
	v_mov_b32_e32 v85, v64
	v_mov_b32_e32 v86, v64
	v_mov_b32_e32 v87, v64
	v_mov_b32_e32 v96, v64
	v_mov_b32_e32 v97, v64
	v_mov_b32_e32 v98, v64
	v_mov_b32_e32 v99, v64
	v_mov_b32_e32 v100, v64
	v_mov_b32_e32 v101, v64
	v_mov_b32_e32 v102, v64
	v_mov_b32_e32 v103, v64
	v_mov_b32_e32 v112, v64
	v_mov_b32_e32 v113, v64
	v_mov_b32_e32 v114, v64
	v_mov_b32_e32 v115, v64
	v_mov_b32_e32 v116, v64
	v_mov_b32_e32 v117, v64
	v_mov_b32_e32 v118, v64
	v_mov_b32_e32 v119, v64
	v_mov_b32_e32 v72, v64
	v_mov_b32_e32 v73, v64
	v_mov_b32_e32 v74, v64
	v_mov_b32_e32 v75, v64
	v_mov_b32_e32 v76, v64
	v_mov_b32_e32 v77, v64
	v_mov_b32_e32 v78, v64
	v_mov_b32_e32 v79, v64
	v_mov_b32_e32 v88, v64
	v_mov_b32_e32 v89, v64
	v_mov_b32_e32 v90, v64
	v_mov_b32_e32 v91, v64
	v_mov_b32_e32 v92, v64
	v_mov_b32_e32 v93, v64
	v_mov_b32_e32 v94, v64
	v_mov_b32_e32 v95, v64
	v_mov_b32_e32 v104, v64
	v_mov_b32_e32 v105, v64
	v_mov_b32_e32 v106, v64
	v_mov_b32_e32 v107, v64
	v_mov_b32_e32 v108, v64
	v_mov_b32_e32 v109, v64
	v_mov_b32_e32 v110, v64
	v_mov_b32_e32 v111, v64
	v_mov_b32_e32 v120, v64
	v_mov_b32_e32 v121, v64
	v_mov_b32_e32 v122, v64
	v_mov_b32_e32 v123, v64
	v_mov_b32_e32 v124, v64
	v_mov_b32_e32 v125, v64
	v_mov_b32_e32 v126, v64
	v_mov_b32_e32 v127, v64
	v_add_u32_e32 v210, 0x10000, v208
	s_branch .LBB0_413
.LBB0_412:
	s_add_i32 s19, s19, 2
	s_add_u32 s8, s8, 0x100
	s_addc_u32 s18, s18, 0
	s_add_u32 s46, s46, 0x100
	s_addc_u32 s47, s47, 0
	s_cmp_gt_u32 s19, 13
	s_barrier
	s_cbranch_scc1 .LBB0_417
.LBB0_413:
	ds_read_b128 v[146:149], v210
	ds_read_b128 v[150:153], v210 offset:1024
	ds_read_b128 v[154:157], v210 offset:2048
	ds_read_b128 v[158:161], v210 offset:3072
	ds_read_b128 v[130:133], v210 offset:16384
	ds_read_b128 v[134:137], v210 offset:17408
	ds_read_b128 v[138:141], v210 offset:18432
	ds_read_b128 v[142:145], v210 offset:19456
	s_mov_b32 s38, m0
	s_mov_b32 m0, s30
	s_nop 0
	global_load_lds_dwordx4 v195, s[46:47]
	s_mov_b32 m0, s38
	s_nop 0
	s_mov_b32 s38, m0
	s_mov_b32 m0, s14
	s_nop 0
	global_load_lds_dwordx4 v197, s[46:47]
	s_mov_b32 m0, s38
	s_add_u32 s38, s46, 0xfffc0080
	s_addc_u32 s39, s47, -1
	s_cmp_eq_u32 s19, 12
	s_cselect_b32 s75, s27, s39
	s_cselect_b32 s74, s99, s38
	s_cselect_b32 s63, s23, s18
	s_cselect_b32 s62, s3, s8
	s_waitcnt lgkmcnt(0)
	ds_read_b128 v[162:165], v209
	ds_read_b128 v[166:169], v209 offset:1024
	ds_read_b128 v[170:173], v209 offset:2048
	ds_read_b128 v[174:177], v209 offset:3072
	ds_read_b128 v[178:181], v209 offset:4096
	ds_read_b128 v[182:185], v209 offset:5120
	ds_read_b128 v[186:189], v209 offset:6144
	ds_read_b128 v[190:193], v209 offset:7168
	s_waitcnt vmcnt(8)
	s_waitcnt lgkmcnt(0)
	s_barrier
	s_setprio 1
	s_waitcnt lgkmcnt(0)
	v_mfma_f32_16x16x32_bf16 v[124:127], v[146:149], v[162:165], v[124:127]
	v_mfma_f32_16x16x32_bf16 v[120:123], v[154:157], v[162:165], v[120:123]
	v_mfma_f32_16x16x32_bf16 v[108:111], v[146:149], v[170:173], v[108:111]
	v_mfma_f32_16x16x32_bf16 v[104:107], v[154:157], v[170:173], v[104:107]
	v_mfma_f32_16x16x32_bf16 v[92:95], v[146:149], v[178:181], v[92:95]
	v_mfma_f32_16x16x32_bf16 v[88:91], v[154:157], v[178:181], v[88:91]
	v_mfma_f32_16x16x32_bf16 v[76:79], v[146:149], v[186:189], v[76:79]
	v_mfma_f32_16x16x32_bf16 v[72:75], v[154:157], v[186:189], v[72:75]
	v_mfma_f32_16x16x32_bf16 v[124:127], v[150:153], v[166:169], v[124:127]
	v_mfma_f32_16x16x32_bf16 v[120:123], v[158:161], v[166:169], v[120:123]
	v_mfma_f32_16x16x32_bf16 v[108:111], v[150:153], v[174:177], v[108:111]
	v_mfma_f32_16x16x32_bf16 v[104:107], v[158:161], v[174:177], v[104:107]
	v_mfma_f32_16x16x32_bf16 v[92:95], v[150:153], v[182:185], v[92:95]
	v_mfma_f32_16x16x32_bf16 v[88:91], v[158:161], v[182:185], v[88:91]
	v_mfma_f32_16x16x32_bf16 v[76:79], v[150:153], v[190:193], v[76:79]
	v_mfma_f32_16x16x32_bf16 v[72:75], v[158:161], v[190:193], v[72:75]
	s_setprio 0
	s_setprio 1
	v_mfma_f32_16x16x32_bf16 v[116:119], v[130:133], v[162:165], v[116:119]
	v_mfma_f32_16x16x32_bf16 v[112:115], v[138:141], v[162:165], v[112:115]
	v_mfma_f32_16x16x32_bf16 v[100:103], v[130:133], v[170:173], v[100:103]
	v_mfma_f32_16x16x32_bf16 v[96:99], v[138:141], v[170:173], v[96:99]
	v_mfma_f32_16x16x32_bf16 v[84:87], v[130:133], v[178:181], v[84:87]
	v_mfma_f32_16x16x32_bf16 v[80:83], v[138:141], v[178:181], v[80:83]
	v_mfma_f32_16x16x32_bf16 v[68:71], v[130:133], v[186:189], v[68:71]
	v_mfma_f32_16x16x32_bf16 v[64:67], v[138:141], v[186:189], v[64:67]
	v_mfma_f32_16x16x32_bf16 v[116:119], v[134:137], v[166:169], v[116:119]
	v_mfma_f32_16x16x32_bf16 v[112:115], v[142:145], v[166:169], v[112:115]
	v_mfma_f32_16x16x32_bf16 v[100:103], v[134:137], v[174:177], v[100:103]
	v_mfma_f32_16x16x32_bf16 v[96:99], v[142:145], v[174:177], v[96:99]
	v_mfma_f32_16x16x32_bf16 v[84:87], v[134:137], v[182:185], v[84:87]
	v_mfma_f32_16x16x32_bf16 v[80:83], v[142:145], v[182:185], v[80:83]
	v_mfma_f32_16x16x32_bf16 v[68:71], v[134:137], v[190:193], v[68:71]
	v_mfma_f32_16x16x32_bf16 v[64:67], v[142:145], v[190:193], v[64:67]
	s_setprio 0
	s_barrier
	s_mov_b32 s38, m0
	s_mov_b32 m0, s67
	s_nop 0
	global_load_lds_dwordx4 v196, s[62:63]
	s_mov_b32 m0, s38
	s_add_u32 s44, s62, 0x40000
	s_mov_b32 s38, m0
	s_mov_b32 m0, s86
	s_nop 0
	global_load_lds_dwordx4 v198, s[62:63]
	s_mov_b32 m0, s38
	s_addc_u32 s45, s63, 0
	s_mov_b32 s38, m0
	s_mov_b32 m0, s87
	s_nop 0
	global_load_lds_dwordx4 v196, s[44:45]
	s_mov_b32 m0, s38
	v_cndmask_b32_e64 v128, 0, 1, s[72:73]
	s_mov_b32 s38, m0
	s_mov_b32 m0, s88
	s_nop 0
	global_load_lds_dwordx4 v198, s[44:45]
	s_mov_b32 m0, s38
	v_cmp_ne_u32_e64 s[44:45], 1, v128
	s_mov_b32 s38, m0
	s_mov_b32 m0, s51
	s_nop 0
	global_load_lds_dwordx4 v195, s[74:75]
	s_mov_b32 m0, s38
	s_andn2_b64 vcc, exec, s[72:73]
	s_mov_b32 s38, m0
	s_mov_b32 m0, s89
	s_nop 0
	global_load_lds_dwordx4 v197, s[74:75]
	s_mov_b32 m0, s38
	ds_read_b128 v[186:189], v209 offset:16384
	ds_read_b128 v[190:193], v209 offset:17408
	ds_read_b128 v[178:181], v209 offset:18432
	ds_read_b128 v[182:185], v209 offset:19456
	ds_read_b128 v[170:173], v209 offset:20480
	ds_read_b128 v[174:177], v209 offset:21504
	ds_read_b128 v[162:165], v209 offset:22528
	ds_read_b128 v[166:169], v209 offset:23552
	s_waitcnt vmcnt(8)
	s_waitcnt lgkmcnt(0)
	s_barrier
	s_cbranch_vccnz .LBB0_415
	s_setprio 1
	s_waitcnt lgkmcnt(0)
	v_mfma_f32_16x16x32_bf16 v[60:63], v[146:149], v[186:189], v[60:63]
	v_mfma_f32_16x16x32_bf16 v[56:59], v[154:157], v[186:189], v[56:59]
	v_mfma_f32_16x16x32_bf16 v[44:47], v[146:149], v[178:181], v[44:47]
	v_mfma_f32_16x16x32_bf16 v[40:43], v[154:157], v[178:181], v[40:43]
	v_mfma_f32_16x16x32_bf16 v[28:31], v[146:149], v[170:173], v[28:31]
	v_mfma_f32_16x16x32_bf16 v[24:27], v[154:157], v[170:173], v[24:27]
	v_mfma_f32_16x16x32_bf16 v[12:15], v[146:149], v[162:165], v[12:15]
	v_mfma_f32_16x16x32_bf16 v[8:11], v[154:157], v[162:165], v[8:11]
	v_mfma_f32_16x16x32_bf16 v[60:63], v[150:153], v[190:193], v[60:63]
	v_mfma_f32_16x16x32_bf16 v[56:59], v[158:161], v[190:193], v[56:59]
	v_mfma_f32_16x16x32_bf16 v[44:47], v[150:153], v[182:185], v[44:47]
	v_mfma_f32_16x16x32_bf16 v[40:43], v[158:161], v[182:185], v[40:43]
	v_mfma_f32_16x16x32_bf16 v[28:31], v[150:153], v[174:177], v[28:31]
	v_mfma_f32_16x16x32_bf16 v[24:27], v[158:161], v[174:177], v[24:27]
	v_mfma_f32_16x16x32_bf16 v[12:15], v[150:153], v[166:169], v[12:15]
	v_mfma_f32_16x16x32_bf16 v[8:11], v[158:161], v[166:169], v[8:11]
	s_setprio 0
	s_setprio 1
	v_mfma_f32_16x16x32_bf16 v[52:55], v[130:133], v[186:189], v[52:55]
	v_mfma_f32_16x16x32_bf16 v[48:51], v[138:141], v[186:189], v[48:51]
	v_mfma_f32_16x16x32_bf16 v[36:39], v[130:133], v[178:181], v[36:39]
	v_mfma_f32_16x16x32_bf16 v[32:35], v[138:141], v[178:181], v[32:35]
	v_mfma_f32_16x16x32_bf16 v[20:23], v[130:133], v[170:173], v[20:23]
	v_mfma_f32_16x16x32_bf16 v[16:19], v[138:141], v[170:173], v[16:19]
	v_mfma_f32_16x16x32_bf16 v[4:7], v[130:133], v[162:165], v[4:7]
	v_mfma_f32_16x16x32_bf16 v[0:3], v[138:141], v[162:165], v[0:3]
	v_mfma_f32_16x16x32_bf16 v[52:55], v[134:137], v[190:193], v[52:55]
	v_mfma_f32_16x16x32_bf16 v[48:51], v[142:145], v[190:193], v[48:51]
	v_mfma_f32_16x16x32_bf16 v[36:39], v[134:137], v[182:185], v[36:39]
	v_mfma_f32_16x16x32_bf16 v[32:35], v[142:145], v[182:185], v[32:35]
	v_mfma_f32_16x16x32_bf16 v[20:23], v[134:137], v[174:177], v[20:23]
	v_mfma_f32_16x16x32_bf16 v[16:19], v[142:145], v[174:177], v[16:19]
	v_mfma_f32_16x16x32_bf16 v[4:7], v[134:137], v[166:169], v[4:7]
	v_mfma_f32_16x16x32_bf16 v[0:3], v[142:145], v[166:169], v[0:3]
	s_setprio 0
.LBB0_415:
	s_add_u32 s76, s74, 0x80
	s_addc_u32 s77, s75, 0
	s_add_u32 s38, s62, 0x80
	s_addc_u32 s39, s63, 0
	s_barrier
	ds_read_b128 v[146:149], v210 offset:32768
	ds_read_b128 v[150:153], v210 offset:33792
	ds_read_b128 v[154:157], v210 offset:34816
	ds_read_b128 v[158:161], v210 offset:35840
	ds_read_b128 v[130:133], v210 offset:49152
	ds_read_b128 v[134:137], v210 offset:50176
	ds_read_b128 v[138:141], v210 offset:51200
	ds_read_b128 v[142:145], v210 offset:52224
	s_add_u32 s74, s74, 0x40000
	s_addc_u32 s75, s75, 0
	s_mov_b32 vcc_lo, m0
	s_mov_b32 m0, s92
	s_nop 0
	global_load_lds_dwordx4 v195, s[74:75]
	s_mov_b32 m0, vcc_lo
	s_nop 0
	s_mov_b32 vcc_lo, m0
	s_mov_b32 m0, s93
	s_nop 0
	global_load_lds_dwordx4 v197, s[74:75]
	s_mov_b32 m0, vcc_lo
	s_waitcnt lgkmcnt(0)
	ds_read_b128 v[162:165], v209 offset:32768
	ds_read_b128 v[166:169], v209 offset:33792
	ds_read_b128 v[170:173], v209 offset:34816
	ds_read_b128 v[174:177], v209 offset:35840
	ds_read_b128 v[178:181], v209 offset:36864
	ds_read_b128 v[182:185], v209 offset:37888
	ds_read_b128 v[186:189], v209 offset:38912
	ds_read_b128 v[190:193], v209 offset:39936
	s_waitcnt vmcnt(8)
	s_waitcnt lgkmcnt(0)
	s_barrier
	s_setprio 1
	s_waitcnt lgkmcnt(0)
	v_mfma_f32_16x16x32_bf16 v[124:127], v[146:149], v[162:165], v[124:127]
	v_mfma_f32_16x16x32_bf16 v[120:123], v[154:157], v[162:165], v[120:123]
	v_mfma_f32_16x16x32_bf16 v[108:111], v[146:149], v[170:173], v[108:111]
	v_mfma_f32_16x16x32_bf16 v[104:107], v[154:157], v[170:173], v[104:107]
	v_mfma_f32_16x16x32_bf16 v[92:95], v[146:149], v[178:181], v[92:95]
	v_mfma_f32_16x16x32_bf16 v[88:91], v[154:157], v[178:181], v[88:91]
	v_mfma_f32_16x16x32_bf16 v[76:79], v[146:149], v[186:189], v[76:79]
	v_mfma_f32_16x16x32_bf16 v[72:75], v[154:157], v[186:189], v[72:75]
	v_mfma_f32_16x16x32_bf16 v[124:127], v[150:153], v[166:169], v[124:127]
	v_mfma_f32_16x16x32_bf16 v[120:123], v[158:161], v[166:169], v[120:123]
	v_mfma_f32_16x16x32_bf16 v[108:111], v[150:153], v[174:177], v[108:111]
	v_mfma_f32_16x16x32_bf16 v[104:107], v[158:161], v[174:177], v[104:107]
	v_mfma_f32_16x16x32_bf16 v[92:95], v[150:153], v[182:185], v[92:95]
	v_mfma_f32_16x16x32_bf16 v[88:91], v[158:161], v[182:185], v[88:91]
	v_mfma_f32_16x16x32_bf16 v[76:79], v[150:153], v[190:193], v[76:79]
	v_mfma_f32_16x16x32_bf16 v[72:75], v[158:161], v[190:193], v[72:75]
	s_setprio 0
	s_setprio 1
	v_mfma_f32_16x16x32_bf16 v[116:119], v[130:133], v[162:165], v[116:119]
	v_mfma_f32_16x16x32_bf16 v[112:115], v[138:141], v[162:165], v[112:115]
	v_mfma_f32_16x16x32_bf16 v[100:103], v[130:133], v[170:173], v[100:103]
	v_mfma_f32_16x16x32_bf16 v[96:99], v[138:141], v[170:173], v[96:99]
	v_mfma_f32_16x16x32_bf16 v[84:87], v[130:133], v[178:181], v[84:87]
	v_mfma_f32_16x16x32_bf16 v[80:83], v[138:141], v[178:181], v[80:83]
	v_mfma_f32_16x16x32_bf16 v[68:71], v[130:133], v[186:189], v[68:71]
	v_mfma_f32_16x16x32_bf16 v[64:67], v[138:141], v[186:189], v[64:67]
	v_mfma_f32_16x16x32_bf16 v[116:119], v[134:137], v[166:169], v[116:119]
	v_mfma_f32_16x16x32_bf16 v[112:115], v[142:145], v[166:169], v[112:115]
	v_mfma_f32_16x16x32_bf16 v[100:103], v[134:137], v[174:177], v[100:103]
	v_mfma_f32_16x16x32_bf16 v[96:99], v[142:145], v[174:177], v[96:99]
	v_mfma_f32_16x16x32_bf16 v[84:87], v[134:137], v[182:185], v[84:87]
	v_mfma_f32_16x16x32_bf16 v[80:83], v[142:145], v[182:185], v[80:83]
	v_mfma_f32_16x16x32_bf16 v[68:71], v[134:137], v[190:193], v[68:71]
	v_mfma_f32_16x16x32_bf16 v[64:67], v[142:145], v[190:193], v[64:67]
	s_setprio 0
	s_barrier
	s_mov_b32 s74, m0
	s_mov_b32 m0, s95
	s_nop 0
	global_load_lds_dwordx4 v196, s[38:39]
	s_mov_b32 m0, s74
	s_nop 0
	s_mov_b32 s74, m0
	s_mov_b32 m0, s96
	s_nop 0
	global_load_lds_dwordx4 v198, s[38:39]
	s_mov_b32 m0, s74
	s_add_u32 s38, s62, 0x40080
	s_addc_u32 s39, s63, 0
	s_mov_b32 s62, m0
	s_mov_b32 m0, s65
	s_nop 0
	global_load_lds_dwordx4 v196, s[38:39]
	s_mov_b32 m0, s62
	s_and_b64 vcc, exec, s[44:45]
	s_mov_b32 s62, m0
	s_mov_b32 m0, s50
	s_nop 0
	global_load_lds_dwordx4 v198, s[38:39]
	s_mov_b32 m0, s62
	s_mov_b32 s38, m0
	s_mov_b32 m0, s97
	s_nop 0
	global_load_lds_dwordx4 v195, s[76:77]
	s_mov_b32 m0, s38
	s_nop 0
	s_mov_b32 s38, m0
	s_mov_b32 m0, s9
	s_nop 0
	global_load_lds_dwordx4 v197, s[76:77]
	s_mov_b32 m0, s38
	ds_read_b128 v[186:189], v209 offset:49152
	ds_read_b128 v[190:193], v209 offset:50176
	ds_read_b128 v[178:181], v209 offset:51200
	ds_read_b128 v[182:185], v209 offset:52224
	ds_read_b128 v[170:173], v209 offset:53248
	ds_read_b128 v[174:177], v209 offset:54272
	ds_read_b128 v[162:165], v209 offset:55296
	ds_read_b128 v[166:169], v209 offset:56320
	s_waitcnt vmcnt(8)
	s_waitcnt lgkmcnt(0)
	s_barrier
	s_cbranch_vccnz .LBB0_412
	s_setprio 1
	s_waitcnt lgkmcnt(0)
	v_mfma_f32_16x16x32_bf16 v[60:63], v[146:149], v[186:189], v[60:63]
	v_mfma_f32_16x16x32_bf16 v[56:59], v[154:157], v[186:189], v[56:59]
	v_mfma_f32_16x16x32_bf16 v[44:47], v[146:149], v[178:181], v[44:47]
	v_mfma_f32_16x16x32_bf16 v[40:43], v[154:157], v[178:181], v[40:43]
	v_mfma_f32_16x16x32_bf16 v[28:31], v[146:149], v[170:173], v[28:31]
	v_mfma_f32_16x16x32_bf16 v[24:27], v[154:157], v[170:173], v[24:27]
	v_mfma_f32_16x16x32_bf16 v[12:15], v[146:149], v[162:165], v[12:15]
	v_mfma_f32_16x16x32_bf16 v[8:11], v[154:157], v[162:165], v[8:11]
	v_mfma_f32_16x16x32_bf16 v[60:63], v[150:153], v[190:193], v[60:63]
	v_mfma_f32_16x16x32_bf16 v[56:59], v[158:161], v[190:193], v[56:59]
	v_mfma_f32_16x16x32_bf16 v[44:47], v[150:153], v[182:185], v[44:47]
	v_mfma_f32_16x16x32_bf16 v[40:43], v[158:161], v[182:185], v[40:43]
	v_mfma_f32_16x16x32_bf16 v[28:31], v[150:153], v[174:177], v[28:31]
	v_mfma_f32_16x16x32_bf16 v[24:27], v[158:161], v[174:177], v[24:27]
	v_mfma_f32_16x16x32_bf16 v[12:15], v[150:153], v[166:169], v[12:15]
	v_mfma_f32_16x16x32_bf16 v[8:11], v[158:161], v[166:169], v[8:11]
	s_setprio 0
	s_setprio 1
	v_mfma_f32_16x16x32_bf16 v[52:55], v[130:133], v[186:189], v[52:55]
	v_mfma_f32_16x16x32_bf16 v[48:51], v[138:141], v[186:189], v[48:51]
	v_mfma_f32_16x16x32_bf16 v[36:39], v[130:133], v[178:181], v[36:39]
	v_mfma_f32_16x16x32_bf16 v[32:35], v[138:141], v[178:181], v[32:35]
	v_mfma_f32_16x16x32_bf16 v[20:23], v[130:133], v[170:173], v[20:23]
	v_mfma_f32_16x16x32_bf16 v[16:19], v[138:141], v[170:173], v[16:19]
	v_mfma_f32_16x16x32_bf16 v[4:7], v[130:133], v[162:165], v[4:7]
	v_mfma_f32_16x16x32_bf16 v[0:3], v[138:141], v[162:165], v[0:3]
	v_mfma_f32_16x16x32_bf16 v[52:55], v[134:137], v[190:193], v[52:55]
	v_mfma_f32_16x16x32_bf16 v[48:51], v[142:145], v[190:193], v[48:51]
	v_mfma_f32_16x16x32_bf16 v[36:39], v[134:137], v[182:185], v[36:39]
	v_mfma_f32_16x16x32_bf16 v[32:35], v[142:145], v[182:185], v[32:35]
	v_mfma_f32_16x16x32_bf16 v[20:23], v[134:137], v[174:177], v[20:23]
	v_mfma_f32_16x16x32_bf16 v[16:19], v[142:145], v[174:177], v[16:19]
	v_mfma_f32_16x16x32_bf16 v[4:7], v[134:137], v[166:169], v[4:7]
	v_mfma_f32_16x16x32_bf16 v[0:3], v[142:145], v[166:169], v[0:3]
	s_setprio 0
	s_branch .LBB0_412
